# XCD-placement guard recorded by wave 0 of each workgroup only, one cache line per barrier group (phase 0 no longer ends behind 4096 same-line atomics)
# speedup vs baseline: 1.0131x; 1.0076x over previous
; DI void phase_prep(const Ctx& c, char* smem) {
;   const Params& p = c.p; (void)p;
;   if (blockIdx.x == 0 && TIDX == 0) { for (int i_ = 0; i_ < 17; ++i_) __hip_atomic_store((unsigned*)(p.ws + OFF_BAR) + 64 * i_, 0u, __ATOMIC_RELAXED, __HIP_MEMORY_SCOPE_AGENT); }
; __global__ void __launch_bounds__(256, 2) mega(Params p, int ph0, int ph1) {
;   extern __shared__ __attribute__((aligned(16))) char smem[];
;   const Ctx c{p, __builtin_amdgcn_readfirstlane((int)(__builtin_amdgcn_workitem_id_x() >> 6))};
;   run_from<0>(c, smem, ph0, ph1);
; }
_Z4mega6Paramsii:
	s_mov_b32 s96, s2
	s_mov_b64 s[74:75], s[0:1]
	s_load_dwordx4 s[92:95], s[0:1], 0x170
	s_load_dwordx16 s[76:91], s[0:1], 0x0
	s_nop 0
	s_load_dwordx16 s[0:15], s[74:75], 0x40
	v_and_b32_e32 v1, 0x3ff, v0
	s_waitcnt lgkmcnt(0)
	s_cmp_gt_i32 s94, 0
	v_readfirstlane_b32 s72, v1
	v_writelane_b32 v253, s0, 0
	s_nop 1
	v_writelane_b32 v253, s1, 1
	v_writelane_b32 v253, s2, 2
	v_writelane_b32 v253, s3, 3
	v_writelane_b32 v253, s4, 4
	v_writelane_b32 v253, s5, 5
	v_writelane_b32 v253, s6, 6
	v_writelane_b32 v253, s7, 7
	v_writelane_b32 v253, s8, 8
	v_writelane_b32 v253, s9, 9
	v_writelane_b32 v253, s10, 10
	v_writelane_b32 v253, s11, 11
	v_writelane_b32 v253, s12, 12
	v_writelane_b32 v253, s13, 13
	v_writelane_b32 v253, s14, 14
	v_writelane_b32 v253, s15, 15
	s_load_dwordx16 s[0:15], s[74:75], 0xc0
	s_waitcnt lgkmcnt(0)
	v_writelane_b32 v253, s0, 16
	s_nop 1
	v_writelane_b32 v253, s1, 17
	v_writelane_b32 v253, s2, 18
	v_writelane_b32 v253, s3, 19
	v_writelane_b32 v253, s4, 20
	v_writelane_b32 v253, s5, 21
	v_writelane_b32 v253, s6, 22
	v_writelane_b32 v253, s7, 23
	v_writelane_b32 v253, s8, 24
	v_writelane_b32 v253, s9, 25
	v_writelane_b32 v253, s10, 26
	v_writelane_b32 v253, s11, 27
	v_writelane_b32 v253, s12, 28
	v_writelane_b32 v253, s13, 29
	v_writelane_b32 v253, s14, 30
	v_writelane_b32 v253, s15, 31
	s_load_dwordx16 s[0:15], s[74:75], 0x100
	s_waitcnt lgkmcnt(0)
	v_writelane_b32 v253, s0, 32
	s_nop 1
	v_writelane_b32 v253, s1, 33
	v_writelane_b32 v253, s2, 34
	v_writelane_b32 v253, s3, 35
	v_writelane_b32 v253, s4, 36
	v_writelane_b32 v253, s5, 37
	v_writelane_b32 v253, s6, 38
	v_writelane_b32 v253, s7, 39
	v_writelane_b32 v253, s8, 40
	v_writelane_b32 v253, s9, 41
	v_writelane_b32 v253, s10, 42
	v_writelane_b32 v253, s11, 43
	v_writelane_b32 v253, s12, 44
	v_writelane_b32 v253, s13, 45
	v_writelane_b32 v253, s14, 46
	v_writelane_b32 v253, s15, 47
	s_cselect_b64 s[0:1], -1, 0
	s_cmp_lt_i32 s95, 1
	s_cselect_b64 s[2:3], -1, 0
	s_or_b64 s[0:1], s[0:1], s[2:3]
	s_and_b64 vcc, exec, s[0:1]
	s_cbranch_vccnz .LBB0_60
	s_cmp_lt_u32 s72, 64
	s_cbranch_scc0 .Lxg_rec
	s_getreg_b32 s98, hwreg(HW_REG_XCC_ID)
	s_and_b32 s98, s98, 15
	s_and_b32 s99, s96, 7
	s_lshl_b32 s99, s99, 8
	s_add_u32 s99, s99, 0x1fe00080
	s_mov_b64 s[100:101], exec
	s_mov_b64 exec, 1
	v_mov_b32_e32 v2, s99
	v_mov_b32_e32 v3, s98
	global_atomic_umin v2, v3, s[92:93]
	s_sub_u32 s98, 15, s98
	v_mov_b32_e32 v3, s98
	global_atomic_umin v2, v3, s[92:93] offset:4
	s_mov_b64 exec, s[100:101]
.Lxg_rec:
	s_cmp_eq_u32 s96, 0
	s_cbranch_scc1 .LBB0_6
	v_mbcnt_lo_u32_b32 v2, -1, 0
	v_mbcnt_hi_u32_b32 v22, -1, v2
	s_cbranch_execnz .LBB0_7

; DI void grid_barrier(const Ctx& c, unsigned idx) {
;   const Params& p = c.p; (void)p;
;   asm volatile("s_waitcnt vmcnt(0)" ::: "memory");
;   __syncthreads();
;   if (TIDX == 0) {
;     unsigned* bar = (unsigned*)(p.ws + OFF_BAR);
;     const unsigned G = gridDim.x, grp = blockIdx.x & 7u;
;     const unsigned gsz = (G >> 3) + ((grp < (G & 7u)) ? 1u : 0u);
;     const unsigned ngrp = G < 8u ? G : 8u;
;     __builtin_amdgcn_fence(__ATOMIC_RELEASE, "agent");
;     asm volatile("s_waitcnt vmcnt(0)" ::: "memory");
;     const unsigned old = __hip_atomic_fetch_add(bar + 64 * (1 + grp), 1u, __ATOMIC_RELAXED, __HIP_MEMORY_SCOPE_AGENT);
;     if (old + 1u == idx * gsz) {
.LBB0_330:
	s_cmp_lt_i32 s95, 3
	s_cbranch_scc1 .LBB0_344
	s_and_b32 s99, s96, 7
	s_lshl_b32 s99, s99, 8
	s_add_u32 s99, s99, 0x1fe00080
	s_load_dwordx2 s[100:101], s[92:93], s99
	s_waitcnt vmcnt(0)
	v_sub_u32_e32 v0, 0, v195
	v_cmp_eq_u32_e32 vcc, s28, v0
	s_barrier
	s_and_saveexec_b64 s[0:1], vcc
	s_cbranch_execz .LBB0_343
	s_add_u32 s6, s92, 0x1fe00000
	s_mov_b64 s[4:5], exec
	s_addc_u32 s7, s93, 0
	s_and_b32 s10, s96, 7
	s_waitcnt lgkmcnt(0)
	s_add_u32 s98, s100, s101
	s_cmp_eq_u32 s98, 15
	s_cselect_b32 s98, 1, 0
	v_writelane_b32 v252, s98, 63
	s_cmp_eq_u32 s98, 1
	s_cbranch_scc1 .Lxg0
	buffer_wbl2 sc1
